# first grid barrier: the 16 per-XCC census counter loads issued back-to-back with one wait (were serialised, one round trip each)
# baseline (speedup 1.0000x reference)
.LBB0_253:
	v_readlane_b32 s6, v254, 2
	s_waitcnt lgkmcnt(0)
	v_readlane_b32 s4, v254, 5
	v_readlane_b32 s5, v254, 6
	s_nop 4
	global_load_dword v0, v129, s[4:5] sc1
	v_readlane_b32 s4, v254, 7
	v_readlane_b32 s5, v254, 8
	s_nop 4
	global_load_dword v1, v129, s[4:5] sc1
	v_readlane_b32 s4, v254, 9
	v_readlane_b32 s5, v254, 10
	s_nop 4
	global_load_dword v2, v129, s[4:5] sc1
	v_readlane_b32 s4, v254, 11
	v_readlane_b32 s5, v254, 12
	s_nop 4
	global_load_dword v3, v129, s[4:5] sc1
	v_readlane_b32 s4, v254, 13
	v_readlane_b32 s5, v254, 14
	s_nop 4
	global_load_dword v4, v129, s[4:5] sc1
	v_readlane_b32 s4, v254, 15
	v_readlane_b32 s5, v254, 16
	s_nop 4
	global_load_dword v5, v129, s[4:5] sc1
	v_readlane_b32 s4, v254, 17
	v_readlane_b32 s5, v254, 18
	s_nop 4
	global_load_dword v6, v129, s[4:5] sc1
	v_readlane_b32 s4, v254, 19
	v_readlane_b32 s5, v254, 20
	s_nop 4
	global_load_dword v7, v129, s[4:5] sc1
	v_readlane_b32 s4, v254, 21
	v_readlane_b32 s5, v254, 22
	s_nop 4
	global_load_dword v8, v129, s[4:5] sc1
	v_readlane_b32 s4, v254, 23
	v_readlane_b32 s5, v254, 24
	s_nop 4
	global_load_dword v9, v129, s[4:5] sc1
	v_readlane_b32 s4, v254, 25
	v_readlane_b32 s5, v254, 26
	s_nop 4
	global_load_dword v10, v129, s[4:5] sc1
	v_readlane_b32 s4, v254, 27
	v_readlane_b32 s5, v254, 28
	s_nop 4
	global_load_dword v11, v129, s[4:5] sc1
	v_readlane_b32 s4, v254, 29
	v_readlane_b32 s5, v254, 30
	s_nop 4
	global_load_dword v12, v129, s[4:5] sc1
	v_readlane_b32 s4, v254, 31
	v_readlane_b32 s5, v254, 32
	s_nop 4
	global_load_dword v13, v129, s[4:5] sc1
	v_readlane_b32 s4, v254, 33
	v_readlane_b32 s5, v254, 34
	s_nop 4
	global_load_dword v14, v129, s[4:5] sc1
	v_readlane_b32 s4, v254, 35
	v_readlane_b32 s5, v254, 36
	s_nop 4
	global_load_dword v15, v129, s[4:5] sc1
	s_mov_b64 s[4:5], -1
	s_waitcnt vmcnt(0)
	v_add_u32_e32 v16, v1, v0
	v_add_u32_e32 v16, v16, v2
	v_add_u32_e32 v16, v16, v3
	v_add_u32_e32 v16, v16, v4
	v_add_u32_e32 v16, v16, v5
	v_add_u32_e32 v16, v16, v6
	v_add_u32_e32 v16, v16, v7
	v_add_u32_e32 v16, v16, v8
	v_add_u32_e32 v16, v16, v9
	v_add_u32_e32 v16, v16, v10
	v_add_u32_e32 v16, v16, v11
	v_add_u32_e32 v16, v16, v12
	v_add_u32_e32 v16, v16, v13
	v_add_u32_e32 v16, v16, v14
	v_add_u32_e32 v16, v16, v15
	v_cmp_eq_u32_e32 vcc, s6, v16
	s_mov_b64 s[6:7], -1
	s_cbranch_vccnz .LBB0_252
	s_and_b32 s4, s11, 0xff
	s_cmp_eq_u32 s4, 0
	s_mov_b64 s[4:5], -1
	s_mov_b64 s[8:9], -1
	s_sleep 1
	s_cbranch_scc1 .LBB0_257
	s_and_b64 vcc, exec, s[8:9]
	s_cbranch_vccz .LBB0_252
